# stack29: stack28 + the two remaining sample-NSA PV key-row blocks: 4 probability LDS reads issued together with counted waits
# baseline (speedup 1.0000x reference)
.LBB0_1565:
	s_or_b64 exec, exec, s[0:1]
	v_add_u32_e32 v132, 0, v124
	ds_read_b32 v82, v132
	ds_read_b32 v216, v132 offset:4224
	ds_read_b32 v218, v132 offset:8448
	ds_read_b32 v220, v132 offset:12672
	v_cmp_gt_u32_e64 s[0:1], s22, v131
	s_waitcnt lgkmcnt(3)
	v_pk_fma_f32 v[68:69], v[36:37], v[82:83], v[68:69] op_sel_hi:[1,0,1]
	v_pk_fma_f32 v[66:67], v[34:35], v[82:83], v[66:67] op_sel_hi:[1,0,1]
	s_waitcnt lgkmcnt(2)
	v_pk_fma_f32 v[80:81], v[36:37], v[216:217], v[80:81] op_sel_hi:[1,0,1]
	v_pk_fma_f32 v[78:79], v[34:35], v[216:217], v[78:79] op_sel_hi:[1,0,1]
	s_waitcnt lgkmcnt(1)
	v_pk_fma_f32 v[76:77], v[36:37], v[218:219], v[76:77] op_sel_hi:[1,0,1]
	v_pk_fma_f32 v[74:75], v[34:35], v[218:219], v[74:75] op_sel_hi:[1,0,1]
	s_waitcnt lgkmcnt(0)
	v_pk_fma_f32 v[72:73], v[36:37], v[220:221], v[72:73] op_sel_hi:[1,0,1]
	v_pk_fma_f32 v[70:71], v[34:35], v[220:221], v[70:71] op_sel_hi:[1,0,1]
	s_and_saveexec_b64 s[6:7], s[0:1]
	s_cbranch_execz .LBB0_1573
	ds_read_b32 v82, v132 offset:128
	ds_read_b32 v216, v132 offset:4352
	ds_read_b32 v218, v132 offset:8576
	ds_read_b32 v220, v132 offset:12800
	s_waitcnt vmcnt(6) lgkmcnt(3)
	v_pk_fma_f32 v[68:69], v[40:41], v[82:83], v[68:69] op_sel_hi:[1,0,1]
	v_pk_fma_f32 v[66:67], v[38:39], v[82:83], v[66:67] op_sel_hi:[1,0,1]
	s_waitcnt lgkmcnt(2)
	v_pk_fma_f32 v[80:81], v[40:41], v[216:217], v[80:81] op_sel_hi:[1,0,1]
	v_pk_fma_f32 v[78:79], v[38:39], v[216:217], v[78:79] op_sel_hi:[1,0,1]
	s_waitcnt lgkmcnt(1)
	v_pk_fma_f32 v[76:77], v[40:41], v[218:219], v[76:77] op_sel_hi:[1,0,1]
	v_pk_fma_f32 v[74:75], v[38:39], v[218:219], v[74:75] op_sel_hi:[1,0,1]
	s_waitcnt lgkmcnt(0)
	v_pk_fma_f32 v[72:73], v[40:41], v[220:221], v[72:73] op_sel_hi:[1,0,1]
	v_pk_fma_f32 v[70:71], v[38:39], v[220:221], v[70:71] op_sel_hi:[1,0,1]
	s_or_b64 exec, exec, s[6:7]
	v_cmp_gt_u32_e64 s[0:1], s26, v131
	s_and_saveexec_b64 s[6:7], s[0:1]
	s_cbranch_execnz .LBB0_1574

.LBB0_1582:
	s_or_b64 exec, exec, s[6:7]
	ds_read_b32 v82, v132 offset:1024
	ds_read_b32 v216, v132 offset:5248
	ds_read_b32 v218, v132 offset:9472
	ds_read_b32 v220, v132 offset:13696
	v_cmp_gt_u32_e32 vcc, s34, v131
	s_waitcnt vmcnt(7) lgkmcnt(3)
	v_pk_fma_f32 v[68:69], v[4:5], v[82:83], v[68:69] op_sel_hi:[1,0,1]
	v_pk_fma_f32 v[66:67], v[2:3], v[82:83], v[66:67] op_sel_hi:[1,0,1]
	s_waitcnt lgkmcnt(2)
	v_pk_fma_f32 v[80:81], v[4:5], v[216:217], v[80:81] op_sel_hi:[1,0,1]
	v_pk_fma_f32 v[78:79], v[2:3], v[216:217], v[78:79] op_sel_hi:[1,0,1]
	s_waitcnt lgkmcnt(1)
	v_pk_fma_f32 v[76:77], v[4:5], v[218:219], v[76:77] op_sel_hi:[1,0,1]
	v_pk_fma_f32 v[74:75], v[2:3], v[218:219], v[74:75] op_sel_hi:[1,0,1]
	s_waitcnt lgkmcnt(0)
	v_pk_fma_f32 v[72:73], v[4:5], v[220:221], v[72:73] op_sel_hi:[1,0,1]
	v_pk_fma_f32 v[70:71], v[2:3], v[220:221], v[70:71] op_sel_hi:[1,0,1]
	s_and_saveexec_b64 s[6:7], vcc
	s_cbranch_execz .LBB0_1589
	ds_read_b32 v82, v132 offset:1152
	ds_read_b32 v216, v132 offset:5376
	ds_read_b32 v218, v132 offset:9600
	ds_read_b32 v220, v132 offset:13824
	s_waitcnt vmcnt(6) lgkmcnt(3)
	v_pk_fma_f32 v[68:69], v[8:9], v[82:83], v[68:69] op_sel_hi:[1,0,1]
	v_pk_fma_f32 v[66:67], v[6:7], v[82:83], v[66:67] op_sel_hi:[1,0,1]
	s_waitcnt lgkmcnt(2)
	v_pk_fma_f32 v[80:81], v[8:9], v[216:217], v[80:81] op_sel_hi:[1,0,1]
	v_pk_fma_f32 v[78:79], v[6:7], v[216:217], v[78:79] op_sel_hi:[1,0,1]
	s_waitcnt lgkmcnt(1)
	v_pk_fma_f32 v[76:77], v[8:9], v[218:219], v[76:77] op_sel_hi:[1,0,1]
	v_pk_fma_f32 v[74:75], v[6:7], v[218:219], v[74:75] op_sel_hi:[1,0,1]
	s_waitcnt lgkmcnt(0)
	v_pk_fma_f32 v[72:73], v[8:9], v[220:221], v[72:73] op_sel_hi:[1,0,1]
	v_pk_fma_f32 v[70:71], v[6:7], v[220:221], v[70:71] op_sel_hi:[1,0,1]
	s_or_b64 exec, exec, s[6:7]
	v_cmp_gt_u32_e32 vcc, s15, v131
	s_and_saveexec_b64 s[6:7], vcc
	s_cbranch_execnz .LBB0_1590
